# attention loop diet v2: + 32-bit pointer advances, M0 hazard slots filled, redundant adj compare dropped from common path
# baseline (speedup 1.0000x reference)
.LBB0_1125:
	s_waitcnt lgkmcnt(0)
	v_mfma_f32_32x32x16_bf16 v[112:127], v[100:103], v[128:131], v[80:95]
	s_add_i32 s39, s39, 0x8000
	s_add_i32 s37, s37, 1
	v_add_f32_e32 v177, v169, v168
	v_add_u32_e32 v202, s84, v202
	v_add_u32_e32 v204, s72, v204
	s_cmp_eq_u32 s39, 0x228000
	v_mfma_f32_32x32x16_bf16 v[112:127], v[96:99], v[132:135], v[112:127]
	v_mfma_f32_32x32x16_bf16 v[112:127], v[104:107], v[136:139], v[112:127]
	v_mfma_f32_32x32x16_bf16 v[112:127], v[108:111], v[140:143], v[112:127]
	s_cbranch_scc1 .LBB0_1139
.LBB0_1126:
	s_add_i32 s0, s39, 0xfffe8000
	s_and_b32 s36, s0, 0x18000
	v_or_b32_e32 v250, s36, v238
	v_or_b32_e32 v72, s36, v195
	v_add_u32_e32 v64, v72, v234
	v_add_u32_e32 v68, v72, v235
	v_add_u32_e32 v73, v72, v236
	v_add_u32_e32 v76, v72, v237
	v_add_u32_e32 v96, v250, v239
	ds_read_b128 v[64:67], v64 offset:8192
	ds_read_b128 v[68:71], v68 offset:8192
	ds_read_b128 v[72:75], v73 offset:8192
	ds_read_b128 v[76:79], v76 offset:8192
	ds_read_b128 v[172:175], v96 offset:16384
	ds_read_b128 v[144:147], v96 offset:20480
	ds_read_b128 v[148:151], v96 offset:24576
	ds_read_b128 v[152:155], v96 offset:28672
	v_add_u32_e32 v96, v250, v240
	ds_read_b128 v[156:159], v96 offset:16384
	ds_read_b128 v[160:163], v96 offset:20480
	ds_read_b128 v[164:167], v96 offset:24576
	ds_read_b128 v[168:171], v96 offset:28672
	s_and_b32 s40, s39, 0x18000
	s_cmp_gt_u32 s37, 64
	s_cbranch_scc1 .LBB0_1128
	s_add_i32 s0, s40, s19
	s_mov_b32 m0, s0
	s_add_i32 s1, s0, 0x4000
	global_load_lds_dwordx4 v204, s[98:99]
	s_mov_b32 m0, s1
	s_nop 0
	global_load_lds_dwordx4 v202, s[100:101]
.LBB0_1128:
	s_waitcnt lgkmcnt(0)
	v_mfma_f32_32x32x16_bf16 v[96:111], v[64:67], v[128:131], v[80:95]
	v_exp_f32_e32 v210, v112
	v_exp_f32_e32 v212, v113
	v_exp_f32_e32 v214, v114
	v_exp_f32_e32 v216, v115
	v_exp_f32_e32 v211, v120
	v_exp_f32_e32 v213, v121
	v_exp_f32_e32 v215, v122
	v_mfma_f32_32x32x16_bf16 v[96:111], v[68:71], v[132:135], v[96:111]
	v_exp_f32_e32 v217, v123
	v_exp_f32_e32 v220, v116
	v_exp_f32_e32 v222, v117
	v_exp_f32_e32 v224, v118
	v_exp_f32_e32 v226, v119
	v_exp_f32_e32 v221, v124
	v_exp_f32_e32 v223, v125
	v_mfma_f32_32x32x16_bf16 v[96:111], v[72:75], v[136:139], v[96:111]
	v_exp_f32_e32 v225, v126
	v_exp_f32_e32 v227, v127
	v_pk_add_f32 v[64:65], v[210:211], v[212:213]
	v_pk_add_f32 v[66:67], v[214:215], v[216:217]
	v_sub_f32_e32 v219, v201, v201
	v_pk_add_f32 v[64:65], v[64:65], v[66:67]
	v_pk_add_f32 v[66:67], v[220:221], v[222:223]
	v_mfma_f32_32x32x16_bf16 v[96:111], v[76:79], v[140:143], v[96:111]
	v_add_f32_e64 v68, v224, v226
	v_add_f32_e64 v69, v225, v227
	v_cmp_neq_f32_e64 s[0:1], 0, v219
	v_add_f32_e64 v66, v66, v68
	v_add_f32_e64 v67, v67, v69
	v_pk_add_f32 v[64:65], v[64:65], v[66:67]
	s_nop 0
	v_add_f32_e32 v218, v64, v65
	v_cmp_nge_f32_e32 vcc, s97, v218
	s_or_b64 vcc, s[0:1], vcc
	s_cbranch_vccz .LBB0_1130
	v_max_f32_e32 v64, v113, v113
	v_max_f32_e32 v65, v112, v112
	v_max_f32_e32 v64, v65, v64
	v_max_f32_e32 v65, v115, v115
	v_max_f32_e32 v66, v114, v114
	v_max_f32_e32 v65, v66, v65
	v_max_f32_e32 v66, v119, v119
	v_max_f32_e32 v67, v118, v118
	v_max_f32_e32 v66, v67, v66
	v_max3_f32 v66, v116, v117, v66
	v_max3_f32 v64, v64, v65, v66
	v_max_f32_e32 v65, v123, v123
	v_max_f32_e32 v66, v122, v122
	v_max_f32_e32 v65, v66, v65
	v_max_f32_e32 v66, v127, v127
	v_max_f32_e32 v67, v126, v126
	v_max_f32_e32 v66, v67, v66
	v_max3_f32 v65, v120, v121, v65
	v_max3_f32 v66, v124, v125, v66
	v_max3_f32 v64, v64, v65, v66
	v_add_f32_e32 v64, v219, v64
	ds_bpermute_b32 v65, v244, v64
	s_waitcnt lgkmcnt(0)
	v_max3_f32 v67, v64, v65, 0
	v_sub_f32_e32 v64, v67, v219
	v_sub_f32_e32 v65, v112, v64
	v_exp_f32_e32 v210, v65
	v_sub_f32_e32 v65, v113, v64
	v_exp_f32_e32 v212, v65
	v_sub_f32_e32 v65, v114, v64
	v_exp_f32_e32 v214, v65
	v_sub_f32_e32 v65, v115, v64
	v_exp_f32_e32 v216, v65
	v_sub_f32_e32 v65, v116, v64
	v_exp_f32_e32 v211, v65
	v_sub_f32_e32 v65, v117, v64
	v_exp_f32_e32 v213, v65
	v_sub_f32_e32 v65, v118, v64
	v_exp_f32_e32 v215, v65
	v_sub_f32_e32 v65, v120, v64
	v_exp_f32_e32 v112, v65
	v_sub_f32_e32 v65, v121, v64
	v_exp_f32_e32 v114, v65
	v_sub_f32_e32 v65, v122, v64
	v_exp_f32_e32 v113, v65
	v_sub_f32_e32 v65, v123, v64
	v_exp_f32_e32 v115, v65
	v_sub_f32_e32 v65, v124, v64
	v_exp_f32_e32 v116, v65
	v_sub_f32_e32 v65, v125, v64
	v_exp_f32_e32 v120, v65
	v_sub_f32_e32 v65, v126, v64
	v_exp_f32_e32 v117, v65
	v_sub_f32_e32 v65, v127, v64
	v_exp_f32_e32 v121, v65
	v_sub_f32_e32 v64, v119, v64
	v_exp_f32_e64 v66, -v67
	v_exp_f32_e32 v217, v64
	v_pk_add_f32 v[64:65], v[112:113], v[114:115]
	v_pk_add_f32 v[68:69], v[116:117], v[120:121]
	v_pk_add_f32 v[64:65], v[64:65], v[64:65] op_sel:[0,1] op_sel_hi:[1,0]
	v_pk_add_f32 v[68:69], v[68:69], v[68:69] op_sel:[0,1] op_sel_hi:[1,0]
	v_mov_b32_e32 v65, v201
	v_mov_b32_e32 v69, v67
	v_mul_f32_e32 v177, v177, v66
	v_pk_add_f32 v[80:81], v[64:65], v[68:69]
	v_pk_mul_f32 v[62:63], v[62:63], v[66:67] op_sel_hi:[1,0]
	v_pk_mul_f32 v[60:61], v[60:61], v[66:67] op_sel_hi:[1,0]
	v_pk_mul_f32 v[58:59], v[58:59], v[66:67] op_sel_hi:[1,0]
	v_pk_mul_f32 v[56:57], v[56:57], v[66:67] op_sel_hi:[1,0]
	v_pk_mul_f32 v[54:55], v[54:55], v[66:67] op_sel_hi:[1,0]
	v_pk_mul_f32 v[52:53], v[52:53], v[66:67] op_sel_hi:[1,0]
	v_pk_mul_f32 v[50:51], v[50:51], v[66:67] op_sel_hi:[1,0]
	v_pk_mul_f32 v[48:49], v[48:49], v[66:67] op_sel_hi:[1,0]
	v_pk_mul_f32 v[46:47], v[46:47], v[66:67] op_sel_hi:[1,0]
	v_pk_mul_f32 v[44:45], v[44:45], v[66:67] op_sel_hi:[1,0]
	v_pk_mul_f32 v[42:43], v[42:43], v[66:67] op_sel_hi:[1,0]
	v_pk_mul_f32 v[40:41], v[40:41], v[66:67] op_sel_hi:[1,0]
	v_pk_mul_f32 v[38:39], v[38:39], v[66:67] op_sel_hi:[1,0]
	v_pk_mul_f32 v[36:37], v[36:37], v[66:67] op_sel_hi:[1,0]
	v_pk_mul_f32 v[34:35], v[34:35], v[66:67] op_sel_hi:[1,0]
	v_pk_mul_f32 v[32:33], v[32:33], v[66:67] op_sel_hi:[1,0]
	v_pk_mul_f32 v[30:31], v[30:31], v[66:67] op_sel_hi:[1,0]
	v_pk_mul_f32 v[28:29], v[28:29], v[66:67] op_sel_hi:[1,0]
	v_pk_mul_f32 v[26:27], v[26:27], v[66:67] op_sel_hi:[1,0]
	v_pk_mul_f32 v[24:25], v[24:25], v[66:67] op_sel_hi:[1,0]
	v_pk_mul_f32 v[22:23], v[22:23], v[66:67] op_sel_hi:[1,0]
	v_pk_mul_f32 v[20:21], v[20:21], v[66:67] op_sel_hi:[1,0]
	v_pk_mul_f32 v[18:19], v[18:19], v[66:67] op_sel_hi:[1,0]
	v_pk_mul_f32 v[16:17], v[16:17], v[66:67] op_sel_hi:[1,0]
	v_pk_mul_f32 v[14:15], v[14:15], v[66:67] op_sel_hi:[1,0]
	v_pk_mul_f32 v[12:13], v[12:13], v[66:67] op_sel_hi:[1,0]
	v_pk_mul_f32 v[10:11], v[10:11], v[66:67] op_sel_hi:[1,0]
	v_pk_mul_f32 v[8:9], v[8:9], v[66:67] op_sel_hi:[1,0]
	v_pk_mul_f32 v[6:7], v[6:7], v[66:67] op_sel_hi:[1,0]
	v_pk_mul_f32 v[4:5], v[4:5], v[66:67] op_sel_hi:[1,0]
	v_pk_mul_f32 v[2:3], v[2:3], v[66:67] op_sel_hi:[1,0]
	v_pk_mul_f32 v[0:1], v[0:1], v[66:67] op_sel_hi:[1,0]
	v_pk_add_f32 v[66:67], v[214:215], v[216:217]
	v_pk_add_f32 v[68:69], v[210:211], v[212:213]
	v_xor_b32_e32 v64, 0x80000000, v81
	v_pk_add_f32 v[66:67], v[68:69], v[66:67]
	v_mov_b32_e32 v65, v64
	v_pk_add_f32 v[66:67], v[66:67], v[66:67] op_sel:[0,1] op_sel_hi:[1,0]
	v_mov_b32_e32 v68, v64
	v_mov_b32_e32 v67, v201
	v_pk_add_f32 v[218:219], v[66:67], v[80:81] neg_lo:[0,1] neg_hi:[0,1]
	v_mov_b32_e32 v67, v64
	v_add_f32_e32 v218, v66, v80
	v_mov_b32_e32 v66, v64
	v_mov_b32_e32 v69, v64
	v_mov_b32_e32 v70, v64
	v_mov_b32_e32 v71, v64
	v_mov_b32_e32 v72, v64
	v_mov_b32_e32 v73, v64
	v_mov_b32_e32 v74, v64
	v_mov_b32_e32 v75, v64
	v_mov_b32_e32 v76, v64
	v_mov_b32_e32 v77, v64
	v_mov_b32_e32 v78, v64
	v_mov_b32_e32 v79, v64
	v_mov_b32_e32 v201, v81
	v_mov_b32_e32 v80, v64
	v_mov_b32_e32 v81, v64
	v_mov_b32_e32 v82, v64
	v_mov_b32_e32 v83, v64
	v_mov_b32_e32 v84, v64
	v_mov_b32_e32 v85, v64
	v_mov_b32_e32 v86, v64
	v_mov_b32_e32 v87, v64
	v_mov_b32_e32 v88, v64
	v_mov_b32_e32 v89, v64
	v_mov_b32_e32 v90, v64
	v_mov_b32_e32 v91, v64
	v_mov_b32_e32 v92, v64
	v_mov_b32_e32 v93, v64
	v_mov_b32_e32 v94, v64
	v_mov_b32_e32 v95, v64
	v_mov_b32_e32 v220, v211
	v_mov_b32_e32 v222, v213
	v_mov_b32_e32 v224, v215
	v_mov_b32_e32 v226, v217
	v_mov_b32_e32 v211, v112
	v_mov_b32_e32 v213, v114
	v_mov_b32_e32 v215, v113
	v_mov_b32_e32 v217, v115
	v_mov_b32_e32 v221, v116
	v_mov_b32_e32 v223, v120
	v_mov_b32_e32 v225, v117
	v_mov_b32_e32 v227, v121
	v_cmp_neq_f32_e64 s[0:1], 0, v219
	s_branch .LBB0_1131
.LBB0_1130:
.LBB0_1131:
	v_cvt_pk_bf16_f32 v112, v210, v212
	v_cvt_pk_bf16_f32 v113, v214, v216
	v_cvt_pk_bf16_f32 v114, v220, v222
	v_cvt_pk_bf16_f32 v115, v224, v226
	v_cvt_pk_bf16_f32 v116, v211, v213
	v_cvt_pk_bf16_f32 v117, v215, v217
	v_mfma_f32_32x32x16_bf16 v[32:47], v[144:147], v[112:115], v[32:47]
	v_cvt_pk_bf16_f32 v118, v221, v223
	v_cvt_pk_bf16_f32 v119, v225, v227
	v_exp_f32_e32 v210, v97
	v_exp_f32_e32 v212, v98
	v_exp_f32_e32 v214, v99
	v_exp_f32_e32 v211, v101
	v_exp_f32_e32 v213, v102
	v_mfma_f32_32x32x16_bf16 v[16:31], v[148:151], v[112:115], v[16:31]
	v_exp_f32_e32 v215, v103
	v_mfma_f32_32x32x16_bf16 v[48:63], v[172:175], v[112:115], v[48:63]
	v_exp_f32_e32 v174, v96
	v_exp_f32_e32 v175, v100
	v_mfma_f32_32x32x16_bf16 v[0:15], v[152:155], v[112:115], v[0:15]
	v_add_u32_e32 v112, v250, v241
	v_mfma_f32_32x32x16_bf16 v[32:47], v[160:163], v[116:119], v[32:47]
	v_exp_f32_e32 v160, v104
	v_exp_f32_e32 v162, v105
	v_exp_f32_e32 v161, v108
	v_exp_f32_e32 v163, v109
	v_mfma_f32_32x32x16_bf16 v[16:31], v[164:167], v[116:119], v[16:31]
	v_exp_f32_e32 v164, v106
	v_exp_f32_e32 v166, v107
	v_exp_f32_e32 v165, v110
	v_exp_f32_e32 v167, v111
	s_nop 0
	v_pk_add_f32 v[172:173], v[164:165], v[166:167]
	v_mfma_f32_32x32x16_bf16 v[48:63], v[156:159], v[116:119], v[48:63]
	ds_read_b128 v[156:159], v112 offset:16384
	ds_read_b128 v[152:155], v112 offset:20480
	ds_read_b128 v[148:151], v112 offset:24576
	ds_read_b128 v[144:147], v112 offset:28672
	v_add_u32_e32 v112, v250, v242
	v_mfma_f32_32x32x16_bf16 v[0:15], v[168:171], v[116:119], v[0:15]
	v_add_f32_e64 v168, v174, v210
	v_add_f32_e64 v169, v175, v211
	v_add_f32_e64 v170, v212, v214
	v_add_f32_e64 v171, v213, v215
	ds_read_b128 v[124:127], v112 offset:16384
	ds_read_b128 v[120:123], v112 offset:20480
	ds_read_b128 v[116:119], v112 offset:24576
	ds_read_b128 v[112:115], v112 offset:28672
	v_pk_add_f32 v[168:169], v[168:169], v[170:171]
	v_pk_add_f32 v[170:171], v[160:161], v[162:163]
	v_pk_add_f32 v[168:169], v[168:169], v[168:169] op_sel:[0,1] op_sel_hi:[1,0]
	v_pk_add_f32 v[170:171], v[170:171], v[172:173]
	v_mov_b32_e32 v169, v177
	v_pk_add_f32 v[170:171], v[170:171], v[170:171] op_sel:[0,1] op_sel_hi:[1,0]
	s_nop 0
	v_mov_b32_e32 v171, v218
	v_pk_add_f32 v[168:169], v[168:169], v[170:171]
	s_nop 0
	v_cmp_nge_f32_e32 vcc, s97, v168
	s_or_b64 vcc, vcc, s[0:1]
	s_cbranch_vccz .LBB0_1133
	v_max_f32_e32 v64, v97, v97
	v_max_f32_e32 v65, v96, v96
	v_max_f32_e32 v64, v65, v64
	v_max_f32_e32 v65, v99, v99
	v_max_f32_e32 v66, v98, v98
	v_max_f32_e32 v65, v66, v65
	v_max_f32_e32 v66, v103, v103
	v_max_f32_e32 v67, v102, v102
	v_max_f32_e32 v66, v67, v66
	v_max3_f32 v66, v100, v101, v66
	v_max3_f32 v64, v64, v65, v66
	v_max_f32_e32 v65, v107, v107
	v_max_f32_e32 v66, v106, v106
	v_max_f32_e32 v65, v66, v65
	v_max_f32_e32 v66, v111, v111
	v_max_f32_e32 v67, v110, v110
	v_max_f32_e32 v66, v67, v66
	v_max3_f32 v65, v104, v105, v65
	v_max3_f32 v66, v108, v109, v66
	v_max3_f32 v64, v64, v65, v66
	v_add_f32_e32 v64, v64, v219
	ds_bpermute_b32 v65, v244, v64
	s_waitcnt lgkmcnt(0)
	v_max3_f32 v64, v64, v65, 0
	v_sub_f32_e32 v67, v64, v219
	v_sub_f32_e32 v68, v96, v67
	v_exp_f32_e32 v96, v68
	v_sub_f32_e32 v68, v97, v67
	v_exp_f32_e32 v170, v68
	v_sub_f32_e32 v68, v98, v67
	v_exp_f32_e32 v98, v68
	v_sub_f32_e32 v68, v99, v67
	v_exp_f32_e32 v172, v68
	v_sub_f32_e32 v68, v100, v67
	v_exp_f32_e32 v160, v68
	v_sub_f32_e32 v68, v101, v67
	v_exp_f32_e32 v162, v68
	v_sub_f32_e32 v68, v102, v67
	v_exp_f32_e32 v164, v68
	v_sub_f32_e32 v68, v103, v67
	v_exp_f32_e32 v166, v68
	v_sub_f32_e32 v68, v104, v67
	v_exp_f32_e32 v97, v68
	v_sub_f32_e32 v68, v105, v67
	v_exp_f32_e32 v171, v68
	v_sub_f32_e32 v68, v106, v67
	v_exp_f32_e32 v99, v68
	v_sub_f32_e32 v68, v107, v67
	v_exp_f32_e32 v173, v68
	v_sub_f32_e32 v68, v108, v67
	v_exp_f32_e32 v161, v68
	v_sub_f32_e32 v68, v109, v67
	v_exp_f32_e32 v163, v68
	v_sub_f32_e32 v68, v110, v67
	v_sub_f32_e32 v67, v111, v67
	v_exp_f32_e32 v165, v68
	v_exp_f32_e32 v167, v67
	v_exp_f32_e64 v66, -v64
	v_pk_add_f32 v[68:69], v[160:161], v[162:163]
	v_add_f32_e32 v201, v201, v64
	v_pk_add_f32 v[70:71], v[164:165], v[166:167]
	v_mul_f32_e32 v65, v169, v66
	v_pk_mul_f32 v[62:63], v[62:63], v[66:67] op_sel_hi:[1,0]
	v_pk_mul_f32 v[60:61], v[60:61], v[66:67] op_sel_hi:[1,0]
	v_pk_mul_f32 v[58:59], v[58:59], v[66:67] op_sel_hi:[1,0]
	v_pk_mul_f32 v[56:57], v[56:57], v[66:67] op_sel_hi:[1,0]
	v_pk_mul_f32 v[54:55], v[54:55], v[66:67] op_sel_hi:[1,0]
	v_pk_mul_f32 v[52:53], v[52:53], v[66:67] op_sel_hi:[1,0]
	v_pk_mul_f32 v[50:51], v[50:51], v[66:67] op_sel_hi:[1,0]
	v_pk_mul_f32 v[48:49], v[48:49], v[66:67] op_sel_hi:[1,0]
	v_pk_mul_f32 v[46:47], v[46:47], v[66:67] op_sel_hi:[1,0]
	v_pk_mul_f32 v[44:45], v[44:45], v[66:67] op_sel_hi:[1,0]
	v_pk_mul_f32 v[42:43], v[42:43], v[66:67] op_sel_hi:[1,0]
	v_pk_mul_f32 v[40:41], v[40:41], v[66:67] op_sel_hi:[1,0]
	v_pk_mul_f32 v[38:39], v[38:39], v[66:67] op_sel_hi:[1,0]
	v_pk_mul_f32 v[36:37], v[36:37], v[66:67] op_sel_hi:[1,0]
	v_pk_mul_f32 v[34:35], v[34:35], v[66:67] op_sel_hi:[1,0]
	v_pk_mul_f32 v[32:33], v[32:33], v[66:67] op_sel_hi:[1,0]
	v_pk_mul_f32 v[30:31], v[30:31], v[66:67] op_sel_hi:[1,0]
	v_pk_mul_f32 v[28:29], v[28:29], v[66:67] op_sel_hi:[1,0]
	v_pk_mul_f32 v[26:27], v[26:27], v[66:67] op_sel_hi:[1,0]
	v_pk_mul_f32 v[24:25], v[24:25], v[66:67] op_sel_hi:[1,0]
	v_pk_mul_f32 v[22:23], v[22:23], v[66:67] op_sel_hi:[1,0]
	v_pk_mul_f32 v[20:21], v[20:21], v[66:67] op_sel_hi:[1,0]
	v_pk_mul_f32 v[18:19], v[18:19], v[66:67] op_sel_hi:[1,0]
	v_pk_mul_f32 v[16:17], v[16:17], v[66:67] op_sel_hi:[1,0]
	v_pk_mul_f32 v[14:15], v[14:15], v[66:67] op_sel_hi:[1,0]
	v_pk_mul_f32 v[12:13], v[12:13], v[66:67] op_sel_hi:[1,0]
	v_pk_mul_f32 v[10:11], v[10:11], v[66:67] op_sel_hi:[1,0]
	v_pk_mul_f32 v[8:9], v[8:9], v[66:67] op_sel_hi:[1,0]
	v_pk_mul_f32 v[6:7], v[6:7], v[66:67] op_sel_hi:[1,0]
	v_pk_mul_f32 v[4:5], v[4:5], v[66:67] op_sel_hi:[1,0]
	v_pk_mul_f32 v[2:3], v[2:3], v[66:67] op_sel_hi:[1,0]
	v_pk_mul_f32 v[0:1], v[0:1], v[66:67] op_sel_hi:[1,0]
	v_pk_add_f32 v[66:67], v[98:99], v[172:173]
	v_pk_add_f32 v[68:69], v[68:69], v[70:71]
	v_pk_add_f32 v[70:71], v[96:97], v[170:171]
	v_xor_b32_e32 v64, 0x80000000, v201
	v_pk_add_f32 v[66:67], v[70:71], v[66:67]
	v_mov_b32_e32 v70, v64
	v_pk_add_f32 v[66:67], v[66:67], v[68:69]
	v_mov_b32_e32 v68, v64
	v_pk_add_f32 v[168:169], v[66:67], v[66:67] op_sel:[0,1] op_sel_hi:[1,0]
	v_mov_b32_e32 v66, v64
	v_mov_b32_e32 v169, v65
	v_mov_b32_e32 v65, v64
	v_mov_b32_e32 v67, v64
	v_mov_b32_e32 v69, v64
	v_mov_b32_e32 v71, v64
	v_mov_b32_e32 v72, v64
	v_mov_b32_e32 v73, v64
	v_mov_b32_e32 v74, v64
	v_mov_b32_e32 v75, v64
	v_mov_b32_e32 v76, v64
	v_mov_b32_e32 v77, v64
	v_mov_b32_e32 v78, v64
	v_mov_b32_e32 v79, v64
	v_mov_b32_e32 v80, v64
	v_mov_b32_e32 v81, v64
	v_mov_b32_e32 v82, v64
	v_mov_b32_e32 v83, v64
	v_mov_b32_e32 v84, v64
	v_mov_b32_e32 v85, v64
	v_mov_b32_e32 v86, v64
	v_mov_b32_e32 v87, v64
	v_mov_b32_e32 v88, v64
	v_mov_b32_e32 v89, v64
	v_mov_b32_e32 v90, v64
	v_mov_b32_e32 v91, v64
	v_mov_b32_e32 v92, v64
	v_mov_b32_e32 v93, v64
	v_mov_b32_e32 v94, v64
	v_mov_b32_e32 v95, v64
	v_mov_b32_e32 v174, v96
	v_mov_b32_e32 v210, v170
	v_mov_b32_e32 v212, v98
	v_mov_b32_e32 v214, v172
	v_mov_b32_e32 v175, v160
	v_mov_b32_e32 v211, v162
	v_mov_b32_e32 v213, v164
	v_mov_b32_e32 v215, v166
	v_mov_b32_e32 v160, v97
	v_mov_b32_e32 v162, v171
	v_mov_b32_e32 v164, v99
	v_mov_b32_e32 v166, v173

.LBB0_1135:
.LBB0_1137:
	s_add_i32 s0, s39, 0xffff0000
	s_and_b32 s0, s0, 0x18000
	v_or_b32_e32 v104, s0, v195
	v_add_u32_e32 v96, v104, v234
	v_add_u32_e32 v97, v104, v235
	v_add_u32_e32 v105, v104, v236
	v_add_u32_e32 v108, v104, v237
	s_waitcnt lgkmcnt(0)
	s_barrier
	ds_read_b128 v[100:103], v96
	ds_read_b128 v[96:99], v97
	ds_read_b128 v[104:107], v105
	ds_read_b128 v[108:111], v108
	s_cmp_gt_u32 s37, 64
	s_cbranch_scc1 .LBB0_1125
	s_add_i32 s8, s40, s19
	v_add_u32_e32 v112, 0x20000, v204
	s_add_i32 m0, s8, 0x2000
	s_addk_i32 s8, 0x6000
	global_load_lds_dwordx4 v112, s[98:99]
	s_mov_b32 m0, s8
	v_add_u32_e32 v114, 0x88000, v202
	global_load_lds_dwordx4 v114, s[100:101]
	s_branch .LBB0_1125
